# phase 10 third tile round (32 sample-row tiles) moved into phase 11 on the owning blocks with a per-row-tile 8-block sync; other 480 blocks normalise prompt rows
# baseline (speedup 1.0000x reference)
_Z4mega6Params:
	v_mov_b32_e32 v244, 0
	s_load_dwordx16 s[4:19], s[0:1], 0x140
	s_load_dwordx8 s[88:95], s[0:1], 0x1a0
	s_load_dwordx8 s[80:87], s[0:1], 0x180
	v_and_b32_e32 v218, 0x3ff, v0
	v_cmp_eq_u32_e64 s[96:97], 0, v218
	s_waitcnt lgkmcnt(0)
	v_writelane_b32 v243, s4, 0
	s_nop 1
	v_writelane_b32 v243, s5, 1
	v_writelane_b32 v243, s6, 2
	v_writelane_b32 v243, s7, 3
	v_writelane_b32 v243, s8, 4
	v_writelane_b32 v243, s9, 5
	v_writelane_b32 v243, s10, 6
	v_writelane_b32 v243, s11, 7
	v_writelane_b32 v243, s12, 8
	v_writelane_b32 v243, s13, 9
	v_writelane_b32 v243, s14, 10
	v_writelane_b32 v243, s15, 11
	v_writelane_b32 v243, s16, 12
	v_writelane_b32 v243, s17, 13
	v_writelane_b32 v243, s18, 14
	v_writelane_b32 v243, s19, 15
	s_add_u32 s4, s0, 0x1b8
	s_addc_u32 s5, s1, 0
	s_and_saveexec_b64 s[6:7], s[96:97]
	s_cbranch_execz .LBB0_2
	v_mov_b32_e32 v2, 0
	v_mov_b32_e32 v3, v2
	v_mov_b32_e32 v4, v2
	v_mov_b32_e32 v5, v2
	v_mov_b32_e32 v1, 0x10400
	ds_write_b128 v1, v[2:5]

.Lp10_pre:
	s_and_b32 s3, s2, 7
	s_sub_i32 s0, 0x8b, s3
	s_lshr_b32 s16, s2, 3
	s_and_b32 s17, s0, 0x88
	v_readlane_b32 s0, v244, 0
	s_nop 3
	s_cmp_eq_u32 s0, 2
	s_cbranch_scc1 .Lp10_nolim
	s_cmpk_lg_i32 s94, 0x200
	s_cbranch_scc1 .Lp10_nolim
	s_min_u32 s17, s17, 0x80
.Lp10_nolim:
	s_cmp_ge_u32 s16, s17
	s_cbranch_scc1 .LBB0_1608
	v_lshrrev_b32_e32 v1, 2, v218
	v_lshrrev_b32_e32 v0, 1, v218
	v_and_b32_e32 v1, 12, v1
	s_movk_i32 s0, 0x1c0
	v_and_or_b32 v0, v0, s0, v1
	v_and_b32_e32 v1, 0x4f, v218
	v_and_b32_e32 v2, 16, v218
	v_and_b32_e32 v3, 0x5f, v218
	s_waitcnt vmcnt(25)
	v_bitop3_b32 v4, v1, v218, 16 bitop3:0x72
	v_bitop3_b32 v1, v1, v2, 48 bitop3:0x36
	v_lshlrev_b32_e32 v3, 2, v3
	v_lshlrev_b32_e32 v0, 9, v0
	v_lshlrev_b32_e32 v4, 2, v4
	v_lshlrev_b32_e32 v1, 2, v1
	s_waitcnt vmcnt(7)
	v_add_u32_e32 v170, v3, v0
	v_add_u32_e32 v171, v4, v0
	v_add_u32_e32 v172, v1, v0
	v_mbcnt_lo_u32_b32 v0, -1, 0
	s_lshr_b32 s18, s94, 3
	s_lshl_b32 s19, s3, 7
	s_mov_b32 s11, 0
	v_mov_b32_e32 v129, 0
	s_mov_b32 s20, 0x7ffffc0
	s_movk_i32 s21, 0xa0
	s_mov_b64 s[12:13], 0x100
	v_mbcnt_hi_u32_b32 v173, -1, v0
	s_mov_b32 s4, s16
	s_mov_b32 s22, 0
	v_readlane_b32 s0, v244, 0
	s_nop 3
	s_cmp_eq_u32 s0, 2
	s_cbranch_scc0 .LBB0_1596
	s_mov_b32 s22, 2
	s_add_i32 s4, s16, 0x80
	s_branch .LBB0_1596

.LBB0_1608:
	v_readlane_b32 s0, v244, 0
	s_nop 3
	s_cmp_eq_u32 s0, 2
	s_cbranch_scc1 .Lp11_ret
	s_cmp_lt_i32 s93, 12
	s_cbranch_scc1 .LBB0_1662
	s_waitcnt vmcnt(0)
	s_waitcnt lgkmcnt(0)
	s_barrier
	s_and_saveexec_b64 s[0:1], s[96:97]
	v_readlane_b32 s8, v243, 0
	v_readlane_b32 s22, v243, 14
	v_readlane_b32 s23, v243, 15
	v_readlane_b32 s9, v243, 1
	v_readlane_b32 s10, v243, 2
	v_readlane_b32 s11, v243, 3
	v_readlane_b32 s12, v243, 4
	v_readlane_b32 s13, v243, 5
	v_readlane_b32 s14, v243, 6
	v_readlane_b32 s15, v243, 7
	v_readlane_b32 s16, v243, 8
	v_readlane_b32 s17, v243, 9
	v_readlane_b32 s18, v243, 10
	v_readlane_b32 s19, v243, 11
	v_readlane_b32 s20, v243, 12
	v_readlane_b32 s21, v243, 13
	s_cbranch_execz .LBB0_1661
	v_mov_b32_e32 v0, 0x10400
	s_waitcnt vmcnt(0) expcnt(0) lgkmcnt(0)
	ds_read_b32 v2, v0
	v_mov_b32_e32 v0, 0x10404
	ds_read_b32 v0, v0
	s_waitcnt lgkmcnt(1)
	v_cmp_ne_u32_e32 vcc, 0, v2
	s_cbranch_vccnz .LBB0_1625
	s_add_u32 s4, s22, 0x1000
	s_addc_u32 s5, s23, 0
	s_add_u32 s6, s22, 0x1100
	s_addc_u32 s7, s23, 0
	s_add_u32 s8, s22, 0x1200
	v_readlane_b32 s3, v243, 16
	s_addc_u32 s9, s23, 0
	s_mul_i32 s3, s95, s3
	s_add_u32 s10, s22, 0x1300
	s_mul_i32 s3, s3, s94
	s_addc_u32 s11, s23, 0
	s_mov_b32 s18, 1
	v_mov_b32_e32 v16, 0
	s_branch .LBB0_1613

.LBB0_1662:
	s_cmp_lt_i32 s92, 12
	s_cselect_b64 s[0:1], -1, 0
	s_cmp_gt_i32 s93, 11
	s_cselect_b64 s[4:5], -1, 0
	s_and_b64 s[0:1], s[0:1], s[4:5]
	v_readlane_b32 s12, v243, 0
	s_andn2_b64 vcc, exec, s[0:1]
	v_readlane_b32 s20, v243, 8
	v_readlane_b32 s21, v243, 9
	v_readlane_b32 s26, v243, 14
	v_readlane_b32 s27, v243, 15
	v_readlane_b32 s13, v243, 1
	v_readlane_b32 s14, v243, 2
	v_readlane_b32 s15, v243, 3
	v_readlane_b32 s16, v243, 4
	v_readlane_b32 s17, v243, 5
	v_readlane_b32 s18, v243, 6
	v_readlane_b32 s19, v243, 7
	v_readlane_b32 s22, v243, 10
	v_readlane_b32 s23, v243, 11
	v_readlane_b32 s24, v243, 12
	v_readlane_b32 s25, v243, 13
	s_cbranch_vccnz .LBB0_1720
	s_cmpk_lg_i32 s94, 0x200
	s_cbranch_scc1 .Lp11_orig
	s_and_b32 s0, s2, 7
	s_lshr_b32 s1, s2, 3
	s_cmp_lt_u32 s0, 4
	s_cselect_b32 s3, 1, 0
	s_cmp_lt_u32 s1, 8
	s_cselect_b32 s4, 1, 0
	s_and_b32 s3, s3, s4
	s_cmp_eq_u32 s3, 1
	s_cbranch_scc1 .Lp11_special
	s_lshl_b32 s1, s1, 2
	s_add_i32 s1, s1, s0
	s_add_i32 s1, s1, -4
	s_sub_i32 s3, s2, 32
	s_cmp_ge_u32 s2, 64
	s_cselect_b32 s2, s3, s1
	s_movk_i32 s98, 0x1e0
	s_movk_i32 s99, 0x4000
	s_branch .Lp11_go
.Lp11_orig:
	s_mov_b32 s98, s94
	s_movk_i32 s99, 0x4200
.Lp11_go:
	s_cmp_ge_i32 s2, s99
	s_cbranch_scc1 .LBB0_1666
	v_readlane_b32 s4, v242, 1
	v_lshlrev_b32_e32 v0, 4, v218
	v_mov_b32_e32 v1, 0
	v_readlane_b32 s5, v242, 2
	v_readlane_b32 s6, v242, 3
	v_readlane_b32 s7, v242, 4
	v_readlane_b32 s8, v242, 5
	v_readlane_b32 s9, v242, 6
	v_readlane_b32 s10, v242, 7
	v_readlane_b32 s11, v242, 8
	v_readlane_b32 s12, v242, 9
	v_readlane_b32 s13, v242, 10
	v_readlane_b32 s14, v242, 11
	v_readlane_b32 s15, v242, 12
	v_readlane_b32 s16, v242, 13
	v_readlane_b32 s17, v242, 14
	v_readlane_b32 s18, v242, 15
	v_readlane_b32 s19, v242, 16
	v_lshl_add_u64 v[2:3], s[4:5], 0, v[0:1]
	v_readlane_b32 s4, v243, 49
	v_readlane_b32 s18, v243, 63
	v_readlane_b32 s19, v242, 0
	s_waitcnt vmcnt(25)
	v_mov_b32_e32 v6, 0x21000
	v_mov_b32_e32 v7, 0x31000
	v_lshl_add_u64 v[4:5], s[18:19], 0, v[0:1]
	v_mov_b32_e32 v0, 0x10000
	v_mov_b32_e32 v8, 0x42000
	v_mov_b32_e32 v9, 0x52000
	v_mov_b32_e32 v10, 0x63000
	v_mov_b32_e32 v11, 0x73000
	v_mov_b32_e32 v12, 0x358637bd
	s_mov_b32 s0, 0x800000
	v_readlane_b32 s5, v243, 50
	v_readlane_b32 s6, v243, 51
	v_readlane_b32 s7, v243, 52
	v_readlane_b32 s8, v243, 53
	v_readlane_b32 s9, v243, 54
	v_readlane_b32 s10, v243, 55
	v_readlane_b32 s11, v243, 56
	v_readlane_b32 s12, v243, 57
	v_readlane_b32 s13, v243, 58
	v_readlane_b32 s14, v243, 59
	v_readlane_b32 s15, v243, 60
	v_readlane_b32 s16, v243, 61
	v_readlane_b32 s17, v243, 62
.LBB0_1665:
	s_ashr_i32 s3, s2, 31
	s_lshl_b64 s[4:5], s[2:3], 2
	s_add_u32 s4, s20, s4
	s_addc_u32 s5, s21, s5
	global_load_dword v13, v1, s[4:5]
	global_load_dword v24, v0, s[4:5] offset:2048
	global_load_dword v25, v6, s[4:5]
	global_load_dword v26, v7, s[4:5] offset:2048
	global_load_dword v27, v8, s[4:5]
	global_load_dword v28, v9, s[4:5] offset:2048
	global_load_dword v29, v10, s[4:5]
	global_load_dword v30, v11, s[4:5] offset:2048
	s_waitcnt lgkmcnt(0)
	global_load_dwordx4 v[14:17], v[4:5], off
	s_lshl_b64 s[4:5], s[2:3], 12
	v_lshl_add_u64 v[22:23], v[2:3], 0, s[4:5]
	global_load_dwordx4 v[18:21], v[22:23], off
	s_add_i32 s2, s2, s98
	s_cmp_lt_i32 s2, s99
	s_waitcnt vmcnt(9)
	v_add_f32_e32 v13, 0, v13
	s_waitcnt vmcnt(8)
	v_add_f32_e32 v13, v13, v24
	s_waitcnt vmcnt(7)
	v_add_f32_e32 v13, v13, v25
	s_waitcnt vmcnt(6)
	v_add_f32_e32 v13, v13, v26
	s_waitcnt vmcnt(5)
	v_add_f32_e32 v13, v13, v27
	s_waitcnt vmcnt(4)
	v_add_f32_e32 v13, v13, v28
	s_waitcnt vmcnt(3)
	v_add_f32_e32 v13, v13, v29
	s_waitcnt vmcnt(2)
	v_add_f32_e32 v13, v13, v30
	v_fmamk_f32 v13, v13, 0x3a800000, v12
	v_mul_f32_e32 v24, 0x4b800000, v13
	v_cmp_gt_f32_e32 vcc, s0, v13
	s_nop 1
	v_cndmask_b32_e32 v13, v13, v24, vcc
	v_rsq_f32_e32 v13, v13
	s_nop 0
	v_mul_f32_e32 v24, 0x45800000, v13
	v_cndmask_b32_e32 v24, v13, v24, vcc
	s_waitcnt vmcnt(1)
	v_pk_mul_f32 v[14:15], v[14:15], v[24:25] op_sel_hi:[1,0]
	v_pk_mul_f32 v[16:17], v[16:17], v[24:25] op_sel_hi:[1,0]
	s_waitcnt vmcnt(0)
	v_pk_mul_f32 v[14:15], v[18:19], v[14:15]
	v_pk_mul_f32 v[16:17], v[20:21], v[16:17]
	global_store_dwordx4 v[22:23], v[14:17], off
	s_cbranch_scc1 .LBB0_1665
	s_branch .LBB0_1666
.Lp11_special:
	v_readlane_b32 s80, v242, 17
	v_readlane_b32 s81, v242, 18
	v_readlane_b32 s82, v242, 19
	v_readlane_b32 s83, v242, 20
	v_readlane_b32 s84, v242, 21
	v_readlane_b32 s85, v242, 22
	v_readlane_b32 s86, v242, 23
	v_readlane_b32 s87, v242, 24
	v_readlane_b32 s88, v242, 25
	v_readlane_b32 s89, v242, 26
	v_readlane_b32 s90, v242, 27
	v_readlane_b32 s91, v242, 28
	v_readlane_b32 s92, v242, 29
	v_readlane_b32 s93, v242, 30
	v_readlane_b32 s94, v242, 31
	v_readlane_b32 s95, v242, 32
	v_writelane_b32 v244, 2, 0
	s_branch .Lp10_pre
.Lp11_ret:
	v_writelane_b32 v244, 0, 0
	s_waitcnt vmcnt(0) lgkmcnt(0)
	buffer_wbl2 sc1
	s_waitcnt vmcnt(0) lgkmcnt(0)
	s_barrier
	v_readlane_b32 s22, v243, 14
	v_readlane_b32 s23, v243, 15
	s_and_b32 s4, s2, 7
	s_lshl_b32 s5, s4, 8
	s_add_i32 s5, s5, 0x3700
	s_and_saveexec_b64 s[0:1], s[96:97]
	s_cbranch_execz .Lp11_spun
	v_mov_b32_e32 v0, s5
	v_mov_b32_e32 v1, 1
	global_atomic_add v0, v1, s[22:23]
	s_mov_b32 s3, 0
.Lp11_spin:
	global_load_dword v2, v0, s[22:23] sc1
	s_waitcnt vmcnt(0)
	v_readfirstlane_b32 s6, v2
	s_nop 3
	s_cmp_ge_u32 s6, 8
	s_cbranch_scc1 .Lp11_spun
	s_sleep 1
	s_add_i32 s3, s3, 1
	s_cmp_lt_u32 s3, 0x40000
	s_cbranch_scc1 .Lp11_spin
.Lp11_spun:
	s_or_b64 exec, exec, s[0:1]
	s_waitcnt vmcnt(0)
	s_barrier
	buffer_inv sc1
	v_readlane_b32 s4, v242, 1
	v_readlane_b32 s5, v242, 2
	v_readlane_b32 s6, v243, 63
	v_readlane_b32 s7, v242, 0
	v_readlane_b32 s8, v243, 8
	v_readlane_b32 s9, v243, 9
	v_lshrrev_b32_e32 v0, 6, v218
	s_nop 1
	v_readfirstlane_b32 s10, v0
	s_and_b32 s11, s2, 7
	s_add_i32 s11, s11, 0x80
	s_lshl_b32 s11, s11, 7
	s_lshr_b32 s12, s2, 3
	s_lshl_b32 s12, s12, 4
	s_add_i32 s11, s11, s12
	s_lshl_b32 s10, s10, 2
	s_add_i32 s11, s11, s10
	v_and_b32_e32 v0, 63, v218
	v_lshlrev_b32_e32 v0, 4, v0
	v_mov_b32_e32 v1, 0
	v_mov_b32_e32 v2, 0x10800
	v_mov_b32_e32 v3, 0x21000
	v_mov_b32_e32 v4, 0x31800
	v_mov_b32_e32 v5, 0x42000
	v_mov_b32_e32 v6, 0x52800
	v_mov_b32_e32 v7, 0x63000
	v_mov_b32_e32 v8, 0x73800
	global_load_dwordx4 v[16:19], v0, s[6:7]
	global_load_dwordx4 v[20:23], v0, s[6:7] offset:1024
	global_load_dwordx4 v[24:27], v0, s[6:7] offset:2048
	global_load_dwordx4 v[28:31], v0, s[6:7] offset:3072
	s_add_i32 s12, s11, 0
	s_lshl_b32 s13, s12, 2
	s_add_u32 s14, s8, s13
	s_addc_u32 s15, s9, 0
	global_load_dword v32, v1, s[14:15]
	global_load_dword v33, v2, s[14:15]
	global_load_dword v34, v3, s[14:15]
	global_load_dword v35, v4, s[14:15]
	global_load_dword v36, v5, s[14:15]
	global_load_dword v37, v6, s[14:15]
	global_load_dword v38, v7, s[14:15]
	global_load_dword v39, v8, s[14:15]
	s_lshl_b32 s13, s12, 12
	s_add_u32 s14, s4, s13
	s_addc_u32 s15, s5, 0
	global_load_dwordx4 v[64:67], v0, s[14:15]
	global_load_dwordx4 v[68:71], v0, s[14:15] offset:1024
	global_load_dwordx4 v[72:75], v0, s[14:15] offset:2048
	global_load_dwordx4 v[76:79], v0, s[14:15] offset:3072
	s_add_i32 s12, s11, 1
	s_lshl_b32 s13, s12, 2
	s_add_u32 s14, s8, s13
	s_addc_u32 s15, s9, 0
	global_load_dword v40, v1, s[14:15]
	global_load_dword v41, v2, s[14:15]
	global_load_dword v42, v3, s[14:15]
	global_load_dword v43, v4, s[14:15]
	global_load_dword v44, v5, s[14:15]
	global_load_dword v45, v6, s[14:15]
	global_load_dword v46, v7, s[14:15]
	global_load_dword v47, v8, s[14:15]
	s_lshl_b32 s13, s12, 12
	s_add_u32 s14, s4, s13
	s_addc_u32 s15, s5, 0
	global_load_dwordx4 v[80:83], v0, s[14:15]
	global_load_dwordx4 v[84:87], v0, s[14:15] offset:1024
	global_load_dwordx4 v[88:91], v0, s[14:15] offset:2048
	global_load_dwordx4 v[92:95], v0, s[14:15] offset:3072
	s_add_i32 s12, s11, 2
	s_lshl_b32 s13, s12, 2
	s_add_u32 s14, s8, s13
	s_addc_u32 s15, s9, 0
	global_load_dword v48, v1, s[14:15]
	global_load_dword v49, v2, s[14:15]
	global_load_dword v50, v3, s[14:15]
	global_load_dword v51, v4, s[14:15]
	global_load_dword v52, v5, s[14:15]
	global_load_dword v53, v6, s[14:15]
	global_load_dword v54, v7, s[14:15]
	global_load_dword v55, v8, s[14:15]
	s_lshl_b32 s13, s12, 12
	s_add_u32 s14, s4, s13
	s_addc_u32 s15, s5, 0
	global_load_dwordx4 v[96:99], v0, s[14:15]
	global_load_dwordx4 v[100:103], v0, s[14:15] offset:1024
	global_load_dwordx4 v[104:107], v0, s[14:15] offset:2048
	global_load_dwordx4 v[108:111], v0, s[14:15] offset:3072
	s_add_i32 s12, s11, 3
	s_lshl_b32 s13, s12, 2
	s_add_u32 s14, s8, s13
	s_addc_u32 s15, s9, 0
	global_load_dword v56, v1, s[14:15]
	global_load_dword v57, v2, s[14:15]
	global_load_dword v58, v3, s[14:15]
	global_load_dword v59, v4, s[14:15]
	global_load_dword v60, v5, s[14:15]
	global_load_dword v61, v6, s[14:15]
	global_load_dword v62, v7, s[14:15]
	global_load_dword v63, v8, s[14:15]
	s_lshl_b32 s13, s12, 12
	s_add_u32 s14, s4, s13
	s_addc_u32 s15, s5, 0
	global_load_dwordx4 v[112:115], v0, s[14:15]
	global_load_dwordx4 v[116:119], v0, s[14:15] offset:1024
	global_load_dwordx4 v[120:123], v0, s[14:15] offset:2048
	global_load_dwordx4 v[124:127], v0, s[14:15] offset:3072
	s_waitcnt vmcnt(0)
	v_mov_b32_e32 v12, 0x358637bd
	s_mov_b32 s0, 0x800000
	v_add_f32_e32 v13, 0, v32
	v_add_f32_e32 v13, v13, v33
	v_add_f32_e32 v13, v13, v34
	v_add_f32_e32 v13, v13, v35
	v_add_f32_e32 v13, v13, v36
	v_add_f32_e32 v13, v13, v37
	v_add_f32_e32 v13, v13, v38
	v_add_f32_e32 v13, v13, v39
	v_fmamk_f32 v13, v13, 0x3a800000, v12
	v_mul_f32_e32 v14, 0x4b800000, v13
	v_cmp_gt_f32_e32 vcc, s0, v13
	s_nop 1
	v_cndmask_b32_e32 v13, v13, v14, vcc
	v_rsq_f32_e32 v13, v13
	s_nop 0
	v_mul_f32_e32 v14, 0x45800000, v13
	v_cndmask_b32_e32 v14, v13, v14, vcc
	s_add_i32 s12, s11, 0
	s_lshl_b32 s13, s12, 12
	s_add_u32 s14, s4, s13
	s_addc_u32 s15, s5, 0
	v_pk_mul_f32 v[128:129], v[16:17], v[14:15] op_sel_hi:[1,0]
	v_pk_mul_f32 v[130:131], v[18:19], v[14:15] op_sel_hi:[1,0]
	v_pk_mul_f32 v[64:65], v[64:65], v[128:129]
	v_pk_mul_f32 v[66:67], v[66:67], v[130:131]
	global_store_dwordx4 v0, v[64:67], s[14:15]
	v_pk_mul_f32 v[128:129], v[20:21], v[14:15] op_sel_hi:[1,0]
	v_pk_mul_f32 v[130:131], v[22:23], v[14:15] op_sel_hi:[1,0]
	v_pk_mul_f32 v[68:69], v[68:69], v[128:129]
	v_pk_mul_f32 v[70:71], v[70:71], v[130:131]
	global_store_dwordx4 v0, v[68:71], s[14:15] offset:1024
	v_pk_mul_f32 v[128:129], v[24:25], v[14:15] op_sel_hi:[1,0]
	v_pk_mul_f32 v[130:131], v[26:27], v[14:15] op_sel_hi:[1,0]
	v_pk_mul_f32 v[72:73], v[72:73], v[128:129]
	v_pk_mul_f32 v[74:75], v[74:75], v[130:131]
	global_store_dwordx4 v0, v[72:75], s[14:15] offset:2048
	v_pk_mul_f32 v[128:129], v[28:29], v[14:15] op_sel_hi:[1,0]
	v_pk_mul_f32 v[130:131], v[30:31], v[14:15] op_sel_hi:[1,0]
	v_pk_mul_f32 v[76:77], v[76:77], v[128:129]
	v_pk_mul_f32 v[78:79], v[78:79], v[130:131]
	global_store_dwordx4 v0, v[76:79], s[14:15] offset:3072
	v_add_f32_e32 v13, 0, v40
	v_add_f32_e32 v13, v13, v41
	v_add_f32_e32 v13, v13, v42
	v_add_f32_e32 v13, v13, v43
	v_add_f32_e32 v13, v13, v44
	v_add_f32_e32 v13, v13, v45
	v_add_f32_e32 v13, v13, v46
	v_add_f32_e32 v13, v13, v47
	v_fmamk_f32 v13, v13, 0x3a800000, v12
	v_mul_f32_e32 v14, 0x4b800000, v13
	v_cmp_gt_f32_e32 vcc, s0, v13
	s_nop 1
	v_cndmask_b32_e32 v13, v13, v14, vcc
	v_rsq_f32_e32 v13, v13
	s_nop 0
	v_mul_f32_e32 v14, 0x45800000, v13
	v_cndmask_b32_e32 v14, v13, v14, vcc
	s_add_i32 s12, s11, 1
	s_lshl_b32 s13, s12, 12
	s_add_u32 s14, s4, s13
	s_addc_u32 s15, s5, 0
	v_pk_mul_f32 v[128:129], v[16:17], v[14:15] op_sel_hi:[1,0]
	v_pk_mul_f32 v[130:131], v[18:19], v[14:15] op_sel_hi:[1,0]
	v_pk_mul_f32 v[80:81], v[80:81], v[128:129]
	v_pk_mul_f32 v[82:83], v[82:83], v[130:131]
	global_store_dwordx4 v0, v[80:83], s[14:15]
	v_pk_mul_f32 v[128:129], v[20:21], v[14:15] op_sel_hi:[1,0]
	v_pk_mul_f32 v[130:131], v[22:23], v[14:15] op_sel_hi:[1,0]
	v_pk_mul_f32 v[84:85], v[84:85], v[128:129]
	v_pk_mul_f32 v[86:87], v[86:87], v[130:131]
	global_store_dwordx4 v0, v[84:87], s[14:15] offset:1024
	v_pk_mul_f32 v[128:129], v[24:25], v[14:15] op_sel_hi:[1,0]
	v_pk_mul_f32 v[130:131], v[26:27], v[14:15] op_sel_hi:[1,0]
	v_pk_mul_f32 v[88:89], v[88:89], v[128:129]
	v_pk_mul_f32 v[90:91], v[90:91], v[130:131]
	global_store_dwordx4 v0, v[88:91], s[14:15] offset:2048
	v_pk_mul_f32 v[128:129], v[28:29], v[14:15] op_sel_hi:[1,0]
	v_pk_mul_f32 v[130:131], v[30:31], v[14:15] op_sel_hi:[1,0]
	v_pk_mul_f32 v[92:93], v[92:93], v[128:129]
	v_pk_mul_f32 v[94:95], v[94:95], v[130:131]
	global_store_dwordx4 v0, v[92:95], s[14:15] offset:3072
	v_add_f32_e32 v13, 0, v48
	v_add_f32_e32 v13, v13, v49
	v_add_f32_e32 v13, v13, v50
	v_add_f32_e32 v13, v13, v51
	v_add_f32_e32 v13, v13, v52
	v_add_f32_e32 v13, v13, v53
	v_add_f32_e32 v13, v13, v54
	v_add_f32_e32 v13, v13, v55
	v_fmamk_f32 v13, v13, 0x3a800000, v12
	v_mul_f32_e32 v14, 0x4b800000, v13
	v_cmp_gt_f32_e32 vcc, s0, v13
	s_nop 1
	v_cndmask_b32_e32 v13, v13, v14, vcc
	v_rsq_f32_e32 v13, v13
	s_nop 0
	v_mul_f32_e32 v14, 0x45800000, v13
	v_cndmask_b32_e32 v14, v13, v14, vcc
	s_add_i32 s12, s11, 2
	s_lshl_b32 s13, s12, 12
	s_add_u32 s14, s4, s13
	s_addc_u32 s15, s5, 0
	v_pk_mul_f32 v[128:129], v[16:17], v[14:15] op_sel_hi:[1,0]
	v_pk_mul_f32 v[130:131], v[18:19], v[14:15] op_sel_hi:[1,0]
	v_pk_mul_f32 v[96:97], v[96:97], v[128:129]
	v_pk_mul_f32 v[98:99], v[98:99], v[130:131]
	global_store_dwordx4 v0, v[96:99], s[14:15]
	v_pk_mul_f32 v[128:129], v[20:21], v[14:15] op_sel_hi:[1,0]
	v_pk_mul_f32 v[130:131], v[22:23], v[14:15] op_sel_hi:[1,0]
	v_pk_mul_f32 v[100:101], v[100:101], v[128:129]
	v_pk_mul_f32 v[102:103], v[102:103], v[130:131]
	global_store_dwordx4 v0, v[100:103], s[14:15] offset:1024
	v_pk_mul_f32 v[128:129], v[24:25], v[14:15] op_sel_hi:[1,0]
	v_pk_mul_f32 v[130:131], v[26:27], v[14:15] op_sel_hi:[1,0]
	v_pk_mul_f32 v[104:105], v[104:105], v[128:129]
	v_pk_mul_f32 v[106:107], v[106:107], v[130:131]
	global_store_dwordx4 v0, v[104:107], s[14:15] offset:2048
	v_pk_mul_f32 v[128:129], v[28:29], v[14:15] op_sel_hi:[1,0]
	v_pk_mul_f32 v[130:131], v[30:31], v[14:15] op_sel_hi:[1,0]
	v_pk_mul_f32 v[108:109], v[108:109], v[128:129]
	v_pk_mul_f32 v[110:111], v[110:111], v[130:131]
	global_store_dwordx4 v0, v[108:111], s[14:15] offset:3072
	v_add_f32_e32 v13, 0, v56
	v_add_f32_e32 v13, v13, v57
	v_add_f32_e32 v13, v13, v58
	v_add_f32_e32 v13, v13, v59
	v_add_f32_e32 v13, v13, v60
	v_add_f32_e32 v13, v13, v61
	v_add_f32_e32 v13, v13, v62
	v_add_f32_e32 v13, v13, v63
	v_fmamk_f32 v13, v13, 0x3a800000, v12
	v_mul_f32_e32 v14, 0x4b800000, v13
	v_cmp_gt_f32_e32 vcc, s0, v13
	s_nop 1
	v_cndmask_b32_e32 v13, v13, v14, vcc
	v_rsq_f32_e32 v13, v13
	s_nop 0
	v_mul_f32_e32 v14, 0x45800000, v13
	v_cndmask_b32_e32 v14, v13, v14, vcc
	s_add_i32 s12, s11, 3
	s_lshl_b32 s13, s12, 12
	s_add_u32 s14, s4, s13
	s_addc_u32 s15, s5, 0
	v_pk_mul_f32 v[128:129], v[16:17], v[14:15] op_sel_hi:[1,0]
	v_pk_mul_f32 v[130:131], v[18:19], v[14:15] op_sel_hi:[1,0]
	v_pk_mul_f32 v[112:113], v[112:113], v[128:129]
	v_pk_mul_f32 v[114:115], v[114:115], v[130:131]
	global_store_dwordx4 v0, v[112:115], s[14:15]
	v_pk_mul_f32 v[128:129], v[20:21], v[14:15] op_sel_hi:[1,0]
	v_pk_mul_f32 v[130:131], v[22:23], v[14:15] op_sel_hi:[1,0]
	v_pk_mul_f32 v[116:117], v[116:117], v[128:129]
	v_pk_mul_f32 v[118:119], v[118:119], v[130:131]
	global_store_dwordx4 v0, v[116:119], s[14:15] offset:1024
	v_pk_mul_f32 v[128:129], v[24:25], v[14:15] op_sel_hi:[1,0]
	v_pk_mul_f32 v[130:131], v[26:27], v[14:15] op_sel_hi:[1,0]
	v_pk_mul_f32 v[120:121], v[120:121], v[128:129]
	v_pk_mul_f32 v[122:123], v[122:123], v[130:131]
	global_store_dwordx4 v0, v[120:123], s[14:15] offset:2048
	v_pk_mul_f32 v[128:129], v[28:29], v[14:15] op_sel_hi:[1,0]
	v_pk_mul_f32 v[130:131], v[30:31], v[14:15] op_sel_hi:[1,0]
	v_pk_mul_f32 v[124:125], v[124:125], v[128:129]
	v_pk_mul_f32 v[126:127], v[126:127], v[130:131]
	global_store_dwordx4 v0, v[124:127], s[14:15] offset:3072
	v_readlane_b32 s93, v242, 30
	v_readlane_b32 s92, v242, 29
	s_nop 3
	s_branch .LBB0_1666

	.amdhsa_kernel _Z4mega6Params
		.amdhsa_group_segment_fixed_size 66576
		.amdhsa_private_segment_fixed_size 0
		.amdhsa_kernarg_size 696
		.amdhsa_user_sgpr_count 2
		.amdhsa_user_sgpr_dispatch_ptr 0
		.amdhsa_user_sgpr_queue_ptr 0
		.amdhsa_user_sgpr_kernarg_segment_ptr 1
		.amdhsa_user_sgpr_dispatch_id 0
		.amdhsa_user_sgpr_kernarg_preload_length 0
		.amdhsa_user_sgpr_kernarg_preload_offset 0
		.amdhsa_user_sgpr_private_segment_size 0
		.amdhsa_uses_dynamic_stack 0
		.amdhsa_enable_private_segment 0
		.amdhsa_system_sgpr_workgroup_id_x 1
		.amdhsa_system_sgpr_workgroup_id_y 0
		.amdhsa_system_sgpr_workgroup_id_z 0
		.amdhsa_system_sgpr_workgroup_info 0
		.amdhsa_system_vgpr_workitem_id 2
		.amdhsa_next_free_vgpr 245
		.amdhsa_next_free_sgpr 102
		.amdhsa_accum_offset 248
		.amdhsa_reserve_vcc 1
		.amdhsa_float_round_mode_32 0
		.amdhsa_float_round_mode_16_64 0
		.amdhsa_float_denorm_mode_32 3
		.amdhsa_float_denorm_mode_16_64 3
		.amdhsa_dx10_clamp 1
		.amdhsa_ieee_mode 1
		.amdhsa_fp16_overflow 0
		.amdhsa_tg_split 0
		.amdhsa_exception_fp_ieee_invalid_op 0
		.amdhsa_exception_fp_denorm_src 0
		.amdhsa_exception_fp_ieee_div_zero 0
		.amdhsa_exception_fp_ieee_overflow 0
		.amdhsa_exception_fp_ieee_underflow 0
		.amdhsa_exception_fp_ieee_inexact 0
		.amdhsa_exception_int_div_zero 0
	.end_amdhsa_kernel

amdhsa.kernels:
  - .agpr_count:     0
    .args:
      - .offset:         0
        .size:           440
        .value_kind:     by_value
      - .offset:         440
        .size:           4
        .value_kind:     hidden_block_count_x
      - .offset:         444
        .size:           4
        .value_kind:     hidden_block_count_y
      - .offset:         448
        .size:           4
        .value_kind:     hidden_block_count_z
      - .offset:         452
        .size:           2
        .value_kind:     hidden_group_size_x
      - .offset:         454
        .size:           2
        .value_kind:     hidden_group_size_y
      - .offset:         456
        .size:           2
        .value_kind:     hidden_group_size_z
      - .offset:         458
        .size:           2
        .value_kind:     hidden_remainder_x
      - .offset:         460
        .size:           2
        .value_kind:     hidden_remainder_y
      - .offset:         462
        .size:           2
        .value_kind:     hidden_remainder_z
      - .offset:         480
        .size:           8
        .value_kind:     hidden_global_offset_x
      - .offset:         488
        .size:           8
        .value_kind:     hidden_global_offset_y
      - .offset:         496
        .size:           8
        .value_kind:     hidden_global_offset_z
      - .offset:         504
        .size:           2
        .value_kind:     hidden_grid_dims
      - .offset:         528
        .size:           8
        .value_kind:     hidden_multigrid_sync_arg
    .group_segment_fixed_size: 66576
    .kernarg_segment_align: 8
    .kernarg_segment_size: 696
    .language:       OpenCL C
    .language_version:
      - 2
      - 0
    .max_flat_workgroup_size: 256
    .name:           _Z4mega6Params
    .private_segment_fixed_size: 0
    .sgpr_count:     108
    .sgpr_spill_count: 103
    .symbol:         _Z4mega6Params.kd
    .uniform_work_group_size: 1
    .uses_dynamic_stack: false
    .vgpr_count:     245
    .vgpr_spill_count: 0
    .wavefront_size: 64
